# GLA pass C: state-fragment loads hoisted to the loop header + head-norm reduction batching (on top of header load merge)
# speedup vs baseline: 1.0160x; 1.0160x over previous
.LBB0_762:
	s_ashr_i32 s70, s74, 8
	s_ashr_i32 s71, s70, 31
	s_lshl_b64 s[66:67], s[70:71], 12
	s_and_b32 s3, s72, 0xfc0
	s_or_b32 s66, s66, s3
	s_mul_i32 s3, s67, 0x1800
	s_mul_hi_u32 s34, s66, 0x1800
	s_bfe_u32 s2, s74, 0x20006
	s_add_i32 s34, s34, s3
	s_mul_i32 s3, s66, 0x1800
	s_add_u32 s68, s62, s3
	s_addc_u32 s69, s63, s34
	s_lshl_b32 s56, s2, 7
	v_lshl_add_u64 v[2:3], s[68:69], 0, v[104:105]
	s_lshl_b32 s2, s2, 8
	s_mov_b32 s3, s57
	v_lshl_add_u64 v[2:3], v[2:3], 0, s[2:3]
	v_lshl_add_u64 v[30:31], v[2:3], 0, v[126:127]
	v_add_co_u32_e32 v2, vcc, s76, v30
	s_mov_b32 s2, 0x31000
	s_nop 0
	v_addc_co_u32_e32 v3, vcc, 0, v31, vcc
	v_add_co_u32_e32 v6, vcc, s77, v30
	s_nop 1
	v_addc_co_u32_e32 v7, vcc, 0, v31, vcc
	v_add_co_u32_e32 v10, vcc, s78, v30
	s_nop 1
	v_addc_co_u32_e32 v11, vcc, 0, v31, vcc
	v_add_co_u32_e32 v14, vcc, s79, v30
	s_nop 1
	v_addc_co_u32_e32 v15, vcc, 0, v31, vcc
	v_add_co_u32_e32 v18, vcc, s2, v30
	s_mov_b32 s2, 0x3d000
	s_nop 0
	v_addc_co_u32_e32 v19, vcc, 0, v31, vcc
	v_add_co_u32_e32 v22, vcc, s2, v30
	s_mov_b32 s2, 0x49000
	s_nop 0
	v_addc_co_u32_e32 v23, vcc, 0, v31, vcc
	v_add_co_u32_e32 v26, vcc, s2, v30
	s_mov_b32 s2, 0x55000
	s_nop 0
	v_addc_co_u32_e32 v27, vcc, 0, v31, vcc
	v_add_co_u32_e32 v30, vcc, s2, v30
	s_nop 1
	v_addc_co_u32_e32 v31, vcc, 0, v31, vcc
	global_load_dwordx4 v[2:5], v[2:3], off
	global_load_dwordx4 v[6:9], v[6:7], off
	global_load_dwordx4 v[10:13], v[10:11], off
	global_load_dwordx4 v[14:17], v[14:15], off
	global_load_dwordx4 v[18:21], v[18:19], off
	global_load_dwordx4 v[22:25], v[22:23], off
	global_load_dwordx4 v[26:29], v[26:27], off
	global_load_dwordx4 v[30:33], v[30:31], off
	v_readlane_b32 s42, v253, 61
	v_readlane_b32 s43, v253, 62
	s_lshl_b64 s[2:3], s[70:71], 23
	s_and_b32 s40, s58, 0x1fe000
	s_add_u32 s2, s42, s2
	s_addc_u32 s3, s43, s3
	s_lshl_b32 s40, s40, 1
	s_add_u32 s2, s2, s40
	s_addc_u32 s3, s3, 0
	v_mov_b32_e32 v180, v128
	v_mov_b32_e32 v181, v103
	v_mov_b32_e32 v178, v132
	v_mov_b32_e32 v179, v103
	v_lshl_add_u64 v[158:159], s[2:3], 0, v[180:181]
	v_lshl_add_u64 v[158:159], v[158:159], 0, v[178:179]
	s_mov_b64 s[2:3], 0x18c00000
	v_lshl_add_u64 v[160:161], v[158:159], 0, s[2:3]
	s_mov_b32 s2, 0x18c01000
	v_add_co_u32_e32 v174, vcc, s2, v158
	s_nop 1
	v_addc_co_u32_e32 v175, vcc, 0, v159, vcc
	global_load_dwordx4 v[182:185], v[174:175], off offset:-4096
	global_load_dwordx4 v[186:189], v[160:161], off offset:32
	global_load_dwordx4 v[190:193], v[160:161], off offset:64
	global_load_dwordx4 v[194:197], v[160:161], off offset:96
	global_load_dwordx4 v[198:201], v[174:175], off
	global_load_dwordx4 v[202:205], v[174:175], off offset:32
	global_load_dwordx4 v[206:209], v[174:175], off offset:64
	global_load_dwordx4 v[210:213], v[174:175], off offset:96
	s_mov_b32 s2, 0x18c02000
	v_add_co_u32_e32 v160, vcc, s2, v158
	s_mov_b32 s2, 0x18c03000
	s_nop 0
	v_addc_co_u32_e32 v161, vcc, 0, v159, vcc
	v_add_co_u32_e32 v158, vcc, s2, v158
	s_nop 1
	v_addc_co_u32_e32 v159, vcc, 0, v159, vcc
	global_load_dwordx4 v[214:217], v[158:159], off offset:-4096
	global_load_dwordx4 v[218:221], v[160:161], off offset:32
	global_load_dwordx4 v[222:225], v[160:161], off offset:64
	global_load_dwordx4 v[226:229], v[160:161], off offset:96
	global_load_dwordx4 v[230:233], v[158:159], off
	global_load_dwordx4 v[234:237], v[158:159], off offset:32
	global_load_dwordx4 v[238:241], v[158:159], off offset:64
	global_load_dwordx4 v[242:245], v[158:159], off offset:96
	v_mov_b32_e32 v129, v103
	v_mov_b32_e32 v131, v103
	s_mov_b64 s[2:3], 0xe00
	v_lshl_add_u64 v[150:151], s[68:69], 0, v[102:103]
	v_lshl_add_u64 v[150:151], v[150:151], 0, s[56:57]
	v_lshl_add_u64 v[152:153], v[150:151], 0, v[128:129]
	v_lshl_add_u64 v[150:151], s[68:69], 0, v[130:131]
	v_lshl_add_u64 v[150:151], v[150:151], 0, s[56:57]
	v_lshl_add_u64 v[154:155], v[150:151], 0, v[128:129]
	v_lshl_add_u64 v[156:157], v[154:155], 0, s[2:3]
	v_cndmask_b32_e64 v158, 0, 1, s[64:65]
	global_load_dwordx4 v[50:53], v[152:153], off offset:3072
	global_load_dwordx4 v[162:165], v[154:155], off offset:3584
	v_cmp_ne_u32_e64 s[34:35], 1, v158
	global_load_dwordx4 v[166:169], v[154:155], off offset:3616
	global_load_dwordx4 v[74:77], v[152:153], off offset:3104
	global_load_dwordx4 v[170:173], v[154:155], off offset:3648
	global_load_dwordx4 v[66:69], v[152:153], off offset:3136
	global_load_dwordx4 v[46:49], v[154:155], off offset:3680
	global_load_dwordx4 v[70:73], v[152:153], off offset:3168
	s_andn2_b64 vcc, exec, s[64:65]
	s_cbranch_vccnz .Lgc_noct1
	v_add_co_u32_e32 v156, vcc, 0x30000, v156
	s_nop 1
	v_addc_co_u32_e32 v157, vcc, 0, v157, vcc
	global_load_dwordx4 v[34:37], v[156:157], off
	global_load_dwordx4 v[38:41], v[156:157], off offset:32
	global_load_dwordx4 v[42:45], v[156:157], off offset:64
	global_load_dwordx4 v[54:57], v[156:157], off offset:96

.LBB0_901:
	v_readlane_b32 s40, v253, 59
	s_lshl_b64 s[2:3], s[70:71], 23
	v_readlane_b32 s42, v253, 61
	v_readlane_b32 s43, v253, 62
	s_add_u32 s2, s42, s2
	s_addc_u32 s3, s43, s3
	s_and_b32 s40, s58, 0x1fe000
	s_lshl_b32 s40, s40, 1
	s_add_u32 s2, s2, s40
	s_addc_u32 s3, s3, 0
	v_mov_b32_e32 v129, v103
	v_cvt_pk_bf16_f32 v90, v2, v3
	v_lshl_add_u64 v[2:3], s[2:3], 0, v[128:129]
	v_mov_b32_e32 v133, v103
	v_cvt_pk_bf16_f32 v92, v6, v7
	v_lshl_add_u64 v[6:7], v[2:3], 0, v[132:133]
	s_mov_b64 s[2:3], 0x18c00000
	v_cvt_pk_bf16_f32 v93, v8, v9
	v_lshl_add_u64 v[8:9], v[6:7], 0, s[2:3]
	s_mov_b32 s2, 0x18c01000
	v_cvt_pk_bf16_f32 v86, v10, v11
	v_add_co_u32_e32 v10, vcc, s2, v6
	v_cvt_pk_bf16_f32 v91, v4, v5
	s_nop 0
	v_addc_co_u32_e32 v11, vcc, 0, v7, vcc
	v_cvt_pk_bf16_f32 v78, v18, v19
	v_cvt_pk_bf16_f32 v79, v20, v21
	v_cvt_pk_bf16_f32 v80, v22, v23
	v_cvt_pk_bf16_f32 v81, v24, v25
	v_cvt_pk_bf16_f32 v82, v26, v27
	v_cvt_pk_bf16_f32 v83, v28, v29
	v_cvt_pk_bf16_f32 v84, v30, v31
	v_cvt_pk_bf16_f32 v85, v32, v33
	v_mov_b64_e32 v[2:3], v[182:183]
	v_mov_b64_e32 v[4:5], v[184:185]
	v_mov_b64_e32 v[18:19], v[186:187]
	v_mov_b64_e32 v[20:21], v[188:189]
	v_mov_b64_e32 v[22:23], v[190:191]
	v_mov_b64_e32 v[24:25], v[192:193]
	v_mov_b64_e32 v[26:27], v[194:195]
	v_mov_b64_e32 v[28:29], v[196:197]
	v_mov_b64_e32 v[30:31], v[198:199]
	v_mov_b64_e32 v[32:33], v[200:201]
	v_mov_b64_e32 v[34:35], v[202:203]
	v_mov_b64_e32 v[36:37], v[204:205]
	v_mov_b64_e32 v[38:39], v[206:207]
	v_mov_b64_e32 v[40:41], v[208:209]
	v_mov_b64_e32 v[42:43], v[210:211]
	v_mov_b64_e32 v[44:45], v[212:213]
	s_mov_b32 s2, 0x18c02000
	v_add_co_u32_e32 v8, vcc, s2, v6
	s_mov_b32 s2, 0x18c03000
	s_nop 0
	v_addc_co_u32_e32 v9, vcc, 0, v7, vcc
	v_add_co_u32_e32 v6, vcc, s2, v6
	v_cvt_pk_bf16_f32 v87, v12, v13
	s_nop 0
	v_addc_co_u32_e32 v7, vcc, 0, v7, vcc
	v_mov_b64_e32 v[46:47], v[214:215]
	v_mov_b64_e32 v[48:49], v[216:217]
	v_mov_b64_e32 v[54:55], v[218:219]
	v_mov_b64_e32 v[56:57], v[220:221]
	v_mov_b64_e32 v[58:59], v[222:223]
	v_mov_b64_e32 v[60:61], v[224:225]
	v_mov_b64_e32 v[62:63], v[226:227]
	v_mov_b64_e32 v[64:65], v[228:229]
	v_mov_b64_e32 v[142:143], v[230:231]
	v_mov_b64_e32 v[144:145], v[232:233]
	v_mov_b64_e32 v[146:147], v[234:235]
	v_mov_b64_e32 v[148:149], v[236:237]
	v_mov_b64_e32 v[94:95], v[238:239]
	v_mov_b64_e32 v[96:97], v[240:241]
	v_mov_b64_e32 v[98:99], v[242:243]
	v_mov_b64_e32 v[100:101], v[244:245]
	v_cvt_pk_bf16_f32 v88, v14, v15
	v_cvt_pk_bf16_f32 v89, v16, v17
	s_waitcnt lgkmcnt(0)
	s_waitcnt vmcnt(0)
	s_waitcnt lgkmcnt(0)
	s_barrier
	s_and_b64 vcc, exec, s[34:35]
	v_readlane_b32 s41, v253, 60
	s_waitcnt vmcnt(15)
	v_mfma_f32_32x32x16_bf16 v[2:17], v[50:53], v[2:5], 0
	s_waitcnt vmcnt(14)
	v_mfma_f32_32x32x16_bf16 v[2:17], v[74:77], v[18:21], v[2:17]
	s_waitcnt vmcnt(13)
	v_mfma_f32_32x32x16_bf16 v[2:17], v[66:69], v[22:25], v[2:17]
	s_waitcnt vmcnt(12)
	v_mfma_f32_32x32x16_bf16 v[2:17], v[70:73], v[26:29], v[2:17]
	s_waitcnt vmcnt(11)
	v_mfma_f32_32x32x16_bf16 v[18:33], v[50:53], v[30:33], 0
	s_waitcnt vmcnt(10)
	v_mfma_f32_32x32x16_bf16 v[18:33], v[74:77], v[34:37], v[18:33]
	s_waitcnt vmcnt(9)
	v_mfma_f32_32x32x16_bf16 v[18:33], v[66:69], v[38:41], v[18:33]
	s_waitcnt vmcnt(8)
	v_mfma_f32_32x32x16_bf16 v[18:33], v[70:73], v[42:45], v[18:33]
	s_waitcnt vmcnt(7)
	v_mfma_f32_32x32x16_bf16 v[34:49], v[50:53], v[46:49], 0
	s_waitcnt vmcnt(6)
	v_mfma_f32_32x32x16_bf16 v[34:49], v[74:77], v[54:57], v[34:49]
	s_waitcnt vmcnt(5)
	v_mfma_f32_32x32x16_bf16 v[34:49], v[66:69], v[58:61], v[34:49]
	s_waitcnt vmcnt(4)
	v_mfma_f32_32x32x16_bf16 v[34:49], v[70:73], v[62:65], v[34:49]
	s_waitcnt vmcnt(3)
	v_mfma_f32_32x32x16_bf16 v[50:65], v[50:53], v[142:145], 0
	s_waitcnt vmcnt(2)
	v_mfma_f32_32x32x16_bf16 v[50:65], v[74:77], v[146:149], v[50:65]
	s_waitcnt vmcnt(1)
	v_mfma_f32_32x32x16_bf16 v[50:65], v[66:69], v[94:97], v[50:65]
	s_waitcnt vmcnt(0)
	v_mfma_f32_32x32x16_bf16 v[50:65], v[70:73], v[98:101], v[50:65]
	ds_read_b64_tr_b16 v[74:75], v140
	ds_read_b64_tr_b16 v[76:77], v140 offset:512
	ds_read_b64_tr_b16 v[94:95], v140 offset:1024
	ds_read_b64_tr_b16 v[96:97], v140 offset:1536
	ds_read_b64_tr_b16 v[66:67], v140 offset:2048
	ds_read_b64_tr_b16 v[68:69], v140 offset:2560
	ds_read_b64_tr_b16 v[70:71], v140 offset:3072
	ds_read_b64_tr_b16 v[72:73], v140 offset:3584
	s_waitcnt lgkmcnt(6)
	v_mfma_f32_32x32x16_bf16 v[2:17], v[90:93], v[74:77], v[2:17]
	s_waitcnt lgkmcnt(4)
	v_mfma_f32_32x32x16_bf16 v[2:17], v[86:89], v[94:97], v[2:17]
	s_cbranch_vccnz .LBB0_903
	s_waitcnt lgkmcnt(2)
	v_mfma_f32_32x32x16_bf16 v[2:17], v[78:81], v[66:69], v[2:17]
	s_waitcnt lgkmcnt(0)
	v_mfma_f32_32x32x16_bf16 v[2:17], v[82:85], v[70:73], v[2:17]
